# FFT step A: the 16 filter loads of a channel issued before the 4-iteration loop (one wait) and rotated through it with register moves (stacked)
# baseline (speedup 1.0000x reference)
.LBB0_422:
	s_ashr_i32 s75, s74, 31
	s_lshl_b64 s[6:7], s[74:75], 14
	s_add_u32 s78, s49, s6
	s_addc_u32 s79, s73, s7
	s_add_i32 s84, s74, 0x800
	s_ashr_i32 s85, s84, 31
	s_lshl_b64 s[76:77], s[84:85], 14
	s_add_u32 s80, s49, s76
	s_addc_u32 s81, s73, s77
	s_add_i32 s76, s74, 0x1000
	s_ashr_i32 s77, s76, 31
	s_lshl_b64 s[82:83], s[76:77], 14
	s_add_u32 s82, s49, s82
	v_mov_b32_e32 v28, v1
	s_addc_u32 s83, s73, s83
	s_add_u32 s86, s78, 0x6000000
	v_lshlrev_b32_e32 v2, 2, v28
	v_lshlrev_b32_e32 v8, 5, v28
	s_addc_u32 s87, s79, 0
	v_sub_u32_e32 v9, 0, v8
	v_sub_u32_e32 v10, 0, v2
	s_mov_b32 s23, 0
	s_mov_b64 s[98:99], 0x1000
	v_ashrrev_i32_e32 v3, 31, v2
	v_lshlrev_b64 v[4:5], 1, v[2:3]
	v_lshl_add_u64 v[6:7], s[78:79], 0, v[4:5]
	global_load_dwordx2 v[120:121], v[6:7], off
	v_lshl_add_u64 v[6:7], s[80:81], 0, v[4:5]
	global_load_dwordx2 v[122:123], v[6:7], off
	v_lshl_add_u64 v[6:7], s[86:87], 0, v[4:5]
	global_load_dwordx2 v[124:125], v[6:7], off
	v_lshl_add_u64 v[6:7], s[82:83], 0, v[4:5]
	global_load_dwordx2 v[126:127], v[6:7], off
	v_lshl_add_u64 v[4:5], v[4:5], 0, s[98:99]
	v_lshl_add_u64 v[6:7], s[78:79], 0, v[4:5]
	global_load_dwordx2 v[128:129], v[6:7], off
	v_lshl_add_u64 v[6:7], s[80:81], 0, v[4:5]
	global_load_dwordx2 v[130:131], v[6:7], off
	v_lshl_add_u64 v[6:7], s[86:87], 0, v[4:5]
	global_load_dwordx2 v[132:133], v[6:7], off
	v_lshl_add_u64 v[6:7], s[82:83], 0, v[4:5]
	global_load_dwordx2 v[134:135], v[6:7], off
	v_lshl_add_u64 v[4:5], v[4:5], 0, s[98:99]
	v_lshl_add_u64 v[6:7], s[78:79], 0, v[4:5]
	global_load_dwordx2 v[136:137], v[6:7], off
	v_lshl_add_u64 v[6:7], s[80:81], 0, v[4:5]
	global_load_dwordx2 v[138:139], v[6:7], off
	v_lshl_add_u64 v[6:7], s[86:87], 0, v[4:5]
	global_load_dwordx2 v[140:141], v[6:7], off
	v_lshl_add_u64 v[6:7], s[82:83], 0, v[4:5]
	global_load_dwordx2 v[142:143], v[6:7], off
	v_lshl_add_u64 v[4:5], v[4:5], 0, s[98:99]
	v_lshl_add_u64 v[6:7], s[78:79], 0, v[4:5]
	global_load_dwordx2 v[144:145], v[6:7], off
	v_lshl_add_u64 v[6:7], s[80:81], 0, v[4:5]
	global_load_dwordx2 v[146:147], v[6:7], off
	v_lshl_add_u64 v[6:7], s[86:87], 0, v[4:5]
	global_load_dwordx2 v[148:149], v[6:7], off
	v_lshl_add_u64 v[6:7], s[82:83], 0, v[4:5]
	global_load_dwordx2 v[150:151], v[6:7], off
	s_waitcnt vmcnt(0)
	s_branch .LBB0_424

.LBB0_424:
	v_mov_b32_e32 v14, v120
	v_mov_b32_e32 v15, v121
	v_mov_b32_e32 v16, v122
	v_mov_b32_e32 v17, v123
	v_mov_b32_e32 v4, v124
	v_mov_b32_e32 v5, v125
	v_mov_b32_e32 v6, v126
	v_mov_b32_e32 v7, v127
	v_mov_b32_e32 v120, v128
	v_mov_b32_e32 v121, v129
	v_mov_b32_e32 v122, v130
	v_mov_b32_e32 v123, v131
	v_mov_b32_e32 v124, v132
	v_mov_b32_e32 v125, v133
	v_mov_b32_e32 v126, v134
	v_mov_b32_e32 v127, v135
	v_mov_b32_e32 v128, v136
	v_mov_b32_e32 v129, v137
	v_mov_b32_e32 v130, v138
	v_mov_b32_e32 v131, v139
	v_mov_b32_e32 v132, v140
	v_mov_b32_e32 v133, v141
	v_mov_b32_e32 v134, v142
	v_mov_b32_e32 v135, v143
	v_mov_b32_e32 v136, v144
	v_mov_b32_e32 v137, v145
	v_mov_b32_e32 v138, v146
	v_mov_b32_e32 v139, v147
	v_mov_b32_e32 v140, v148
	v_mov_b32_e32 v141, v149
	v_mov_b32_e32 v142, v150
	v_mov_b32_e32 v143, v151
	v_ashrrev_i32_e32 v11, 9, v2
	v_and_b32_e32 v12, -16, v2
	v_add_u32_e32 v3, s23, v10
	v_lshl_add_u32 v11, v11, 7, v12
	v_add3_u32 v11, 0, v11, v8
	v_cmp_ne_u32_e32 vcc, 0, v3
	s_waitcnt vmcnt(3)
	v_lshlrev_b32_e32 v12, 16, v14
	v_and_b32_e32 v14, 0xffff0000, v14
	v_lshlrev_b32_e32 v30, 16, v15
	v_and_b32_e32 v32, 0xffff0000, v15
	s_waitcnt vmcnt(2)
	v_lshlrev_b32_e32 v13, 16, v16
	v_and_b32_e32 v15, 0xffff0000, v16
	v_lshlrev_b32_e32 v31, 16, v17
	v_and_b32_e32 v33, 0xffff0000, v17
	ds_write_b128 v11, v[12:15]
	ds_write_b128 v11, v[30:33] offset:16
	s_and_saveexec_b64 s[88:89], vcc
	s_xor_b64 s[88:89], exec, s[88:89]
	s_cbranch_execz .LBB0_426
	v_add_u32_e32 v11, 0x4000, v3
	v_ashrrev_i32_e32 v14, 9, v11
	v_lshlrev_b32_e32 v14, 7, v14
	v_and_b32_e32 v11, -16, v11
	v_add3_u32 v11, v14, v11, 0
	s_waitcnt vmcnt(1)
	v_lshlrev_b32_e32 v13, 16, v4
	s_waitcnt vmcnt(0)
	v_lshlrev_b32_e32 v12, 16, v6
	v_add3_u32 v11, v11, v9, s96
	ds_write_b64 v11, v[12:13]

	.amdhsa_kernel _Z8mega_fwd4Args
		.amdhsa_group_segment_fixed_size 0
		.amdhsa_private_segment_fixed_size 0
		.amdhsa_kernarg_size 504
		.amdhsa_user_sgpr_count 2
		.amdhsa_user_sgpr_dispatch_ptr 0
		.amdhsa_user_sgpr_queue_ptr 0
		.amdhsa_user_sgpr_kernarg_segment_ptr 1
		.amdhsa_user_sgpr_dispatch_id 0
		.amdhsa_user_sgpr_kernarg_preload_length 0
		.amdhsa_user_sgpr_kernarg_preload_offset 0
		.amdhsa_user_sgpr_private_segment_size 0
		.amdhsa_uses_dynamic_stack 0
		.amdhsa_enable_private_segment 0
		.amdhsa_system_sgpr_workgroup_id_x 1
		.amdhsa_system_sgpr_workgroup_id_y 0
		.amdhsa_system_sgpr_workgroup_id_z 0
		.amdhsa_system_sgpr_workgroup_info 0
		.amdhsa_system_vgpr_workitem_id 0
		.amdhsa_next_free_vgpr 253
		.amdhsa_next_free_sgpr 100
		.amdhsa_accum_offset 256
		.amdhsa_reserve_vcc 1
		.amdhsa_float_round_mode_32 0
		.amdhsa_float_round_mode_16_64 0
		.amdhsa_float_denorm_mode_32 3
		.amdhsa_float_denorm_mode_16_64 3
		.amdhsa_dx10_clamp 1
		.amdhsa_ieee_mode 1
		.amdhsa_fp16_overflow 0
		.amdhsa_tg_split 0
		.amdhsa_exception_fp_ieee_invalid_op 0
		.amdhsa_exception_fp_denorm_src 0
		.amdhsa_exception_fp_ieee_div_zero 0
		.amdhsa_exception_fp_ieee_overflow 0
		.amdhsa_exception_fp_ieee_underflow 0
		.amdhsa_exception_fp_ieee_inexact 0
		.amdhsa_exception_int_div_zero 0
	.end_amdhsa_kernel

amdhsa.kernels:
  - .agpr_count:     0
    .args:
      - .offset:         0
        .size:           248
        .value_kind:     by_value
      - .offset:         248
        .size:           4
        .value_kind:     hidden_block_count_x
      - .offset:         252
        .size:           4
        .value_kind:     hidden_block_count_y
      - .offset:         256
        .size:           4
        .value_kind:     hidden_block_count_z
      - .offset:         260
        .size:           2
        .value_kind:     hidden_group_size_x
      - .offset:         262
        .size:           2
        .value_kind:     hidden_group_size_y
      - .offset:         264
        .size:           2
        .value_kind:     hidden_group_size_z
      - .offset:         266
        .size:           2
        .value_kind:     hidden_remainder_x
      - .offset:         268
        .size:           2
        .value_kind:     hidden_remainder_y
      - .offset:         270
        .size:           2
        .value_kind:     hidden_remainder_z
      - .offset:         288
        .size:           8
        .value_kind:     hidden_global_offset_x
      - .offset:         296
        .size:           8
        .value_kind:     hidden_global_offset_y
      - .offset:         304
        .size:           8
        .value_kind:     hidden_global_offset_z
      - .offset:         312
        .size:           2
        .value_kind:     hidden_grid_dims
      - .offset:         368
        .size:           4
        .value_kind:     hidden_dynamic_lds_size
    .group_segment_fixed_size: 0
    .kernarg_segment_align: 8
    .kernarg_segment_size: 504
    .language:       OpenCL C
    .language_version:
      - 2
      - 0
    .max_flat_workgroup_size: 512
    .name:           _Z8mega_fwd4Args
    .private_segment_fixed_size: 0
    .sgpr_count:     106
    .sgpr_spill_count: 6
    .symbol:         _Z8mega_fwd4Args.kd
    .uniform_work_group_size: 1
    .uses_dynamic_stack: false
    .vgpr_count:     253
    .vgpr_spill_count: 0
    .wavefront_size: 64
